# K-loop LDS read rebalancing strategy (G copy): next half k-tile's B0 fragment reads issued inside the read-free MMA(1,1) cluster instead of heading the 12-read segment
# baseline (speedup 1.0000x reference)
; __device__ __forceinline__ int lane_fresh() { int l; asm volatile("v_mbcnt_lo_u32_b32 %0, -1, 0\n\tv_mbcnt_hi_u32_b32 %0, -1, %0" : "=v"(l)); return l; }
; #define LDA(dst, b, h) for (int m = 0; m < 4; ++m) for (int k = 0; k < 2; ++k) \
;     dst[m][k] = *reinterpret_cast<const bf16x8*>((char*)SA(b, h) + lds_byte(wr * 64 + m * 16 + fr, k * 32 + fq * 8))
; #define LDB(dst, b, h) for (int n = 0; n < 2; ++n) for (int k = 0; k < 2; ++k) \
;     dst[n][k] = *reinterpret_cast<const bf16x8*>((char*)SB(b, h) + lds_byte(wc * 32 + n * 16 + fr, k * 32 + fq * 8))
; #define WAIT_V(n) asm volatile("s_waitcnt vmcnt(" #n ")" ::: "memory")
; #define WAIT_L(n) asm volatile("s_waitcnt lgkmcnt(" #n ")" ::: "memory")
; #define BAR __builtin_amdgcn_s_barrier()
; #define SCHED __builtin_amdgcn_sched_barrier(0)
; template <int PART  , bool SYNC_FIRST = true>
; __device__ __forceinline__ void kloop_t(const u16* __restrict__ A, int lda, const u16* __restrict__ Bt, int ldb, int K, Acc& acc, const int wv) {
;     ...
;   const int wid = wv, lane = lane_fresh(), ktid = wv * 64 + lane, wr = wid >> 2, wc = wid & 3, fr = lane & 15, fq = lane >> 4;
;   bf16x8 At[4][2], B0[2][2], B1[2][2];
;   const int nt = K / BK;
;   unsigned oA0, oA1, oB0, oB1;
;   { int r_, c_; stage_rc(ktid * 16, r_, c_); oA0 = (unsigned)(r_ * lda + c_) * 2u; oB0 = (unsigned)(r_ * ldb + c_) * 2u;
;     stage_rc(ktid * 16 + 8192, r_, c_); oA1 = (unsigned)(r_ * lda + c_) * 2u; oB1 = (unsigned)(r_ * ldb + c_) * 2u; }
;   if (PART != 2) {
;     if (SYNC_FIRST) { WAIT_V(0); WAIT_L(0); __syncthreads(); }
;     STAGE(SB(0, 0), Bt, ldb, 0, 0); STAGE(SA(0, 0), A, lda, 0, 0);
;     STAGE(SB(0, 1), Bt, ldb, HALF, 0); STAGE(SA(0, 1), A, lda, HALF, 0);
;   }
;   if (PART == 1) return;
;   if (wr == 1) BAR;
;   WAIT_V(4); BAR;
;   STAGE(SB(1, 0), Bt, ldb, 0, 1); STAGE(SA(1, 0), A, lda, 0, 1); STAGE(SB(1, 1), Bt, ldb, HALF, 1);
;   WAIT_V(6); BAR;
; #pragma unroll 1
;   for (int t = 0; t < nt - 2; t += 2) {
;     LDB(B0, 0, 0); SCHED; LDA(At, 0, 0); STAGE(SA(1, 1), A, lda, HALF, t + 1);
.LBB0_1138:
	s_lshr_b32 s44, s85, 6
	s_and_b32 s44, s44, 3
	s_lshl_b32 s55, s44, 21
	s_and_b32 s44, s84, 63
	v_mov_b32_e32 v2, v131
	v_mov_b32_e32 v128, v130
	v_add_u32_e32 v150, s80, v1
	s_lshl_b32 s56, s44, 21
	s_waitcnt vmcnt(4)
	s_barrier
	v_readfirstlane_b32 s44, v150
	v_lshl_add_u64 v[4:5], s[42:43], 0, v[128:129]
	v_mov_b32_e32 v3, v129
	v_add_u32_e32 v151, 0x2000, v150
	v_lshl_add_u64 v[4:5], v[4:5], 0, s[22:23]
	s_mov_b32 m0, s44
	v_lshl_add_u64 v[2:3], s[42:43], 0, v[2:3]
	v_readfirstlane_b32 s44, v151
	global_load_lds_dwordx4 v[4:5], off
	v_lshl_add_u64 v[2:3], v[2:3], 0, s[22:23]
	s_mov_b32 m0, s44
	v_mov_b32_e32 v128, v130
	global_load_lds_dwordx4 v[2:3], off
	v_mov_b32_e32 v2, v131
	v_add_u32_e32 v152, 0x8000, v144
	v_mov_b32_e32 v3, v129
	v_lshl_add_u64 v[4:5], s[4:5], 0, v[128:129]
	v_readfirstlane_b32 s44, v152
	v_add_u32_e32 v153, 0xa000, v144
	v_lshl_add_u64 v[4:5], v[4:5], 0, s[22:23]
	s_mov_b32 m0, s44
	v_lshl_add_u64 v[2:3], s[4:5], 0, v[2:3]
	v_readfirstlane_b32 s44, v153
	v_add_u32_e32 v154, s81, v1
	global_load_lds_dwordx4 v[4:5], off
	v_lshl_add_u64 v[2:3], v[2:3], 0, s[22:23]
	s_mov_b32 m0, s44
	s_add_u32 s42, s42, 0x100080
	v_readfirstlane_b32 s44, v154
	v_add_u32_e32 v155, 0x2000, v154
	global_load_lds_dwordx4 v[2:3], off
	s_addc_u32 s43, s43, 0
	v_mov_b32_e32 v2, v131
	v_mov_b32_e32 v3, v130
	s_mov_b32 m0, s44
	v_readfirstlane_b32 s44, v155
	v_and_b32_e32 v6, 15, v0
	global_load_lds_dwordx4 v3, s[42:43]
	s_mov_b32 m0, s44
	v_lshlrev_b32_e32 v4, 2, v0
	global_load_lds_dwordx4 v2, s[42:43]
	v_lshlrev_b32_e32 v2, 6, v6
	v_and_b32_e32 v3, 48, v0
	v_and_b32_e32 v4, 32, v4
	v_bitop3_b32 v2, v2, v4, v3 bitop3:0x36
	v_ashrrev_i32_e32 v1, 1, v0
	v_add_u32_e32 v156, s78, v2
	v_add_u32_e32 v157, s79, v2
	v_add_u32_e32 v158, s80, v2
	v_add_u32_e32 v159, s81, v2
	v_or_b32_e32 v2, s65, v6
	v_or_b32_e32 v7, s68, v6
	v_or_b32_e32 v10, s70, v6
	v_or_b32_e32 v6, s72, v6
	v_add_u32_e32 v1, 32, v1
	v_lshlrev_b32_e32 v4, 6, v2
	v_lshlrev_b32_e32 v2, 2, v2
	v_lshlrev_b32_e32 v8, 6, v7
	v_lshlrev_b32_e32 v7, 2, v7
	v_lshlrev_b32_e32 v11, 6, v10
	v_lshlrev_b32_e32 v10, 2, v10
	v_lshlrev_b32_e32 v13, 6, v6
	v_lshlrev_b32_e32 v6, 2, v6
	s_waitcnt vmcnt(6)
	v_ashrrev_i32_e32 v0, 6, v0
	v_ashrrev_i32_e32 v1, 5, v1
	v_and_or_b32 v4, v4, s82, v3
	v_and_b32_e32 v2, 32, v2
	v_and_or_b32 v8, v8, s82, v3
	v_and_b32_e32 v7, 32, v7
	v_and_or_b32 v11, v11, s82, v3
	v_and_b32_e32 v10, 32, v10
	v_and_or_b32 v3, v13, s82, v3
	v_and_b32_e32 v6, 32, v6
	v_add_lshl_u32 v160, v0, s64, 10
	v_add_lshl_u32 v161, v1, s64, 10
	v_add_lshl_u32 v162, v0, s66, 10
	v_add_lshl_u32 v163, v1, s66, 10
	v_xad_u32 v2, v4, v2, 16
	v_add_lshl_u32 v4, v0, s67, 10
	v_add_lshl_u32 v5, v1, s67, 10
	v_xad_u32 v7, v8, v7, 16
	v_add_lshl_u32 v8, v0, s69, 10
	v_add_lshl_u32 v9, v1, s69, 10
	v_xad_u32 v10, v11, v10, 16
	v_add_lshl_u32 v11, v0, s71, 10
	v_add_lshl_u32 v12, v1, s71, 10
	v_xad_u32 v3, v3, v6, 16
	v_add_lshl_u32 v6, v0, s73, 10
	v_add_lshl_u32 v1, v1, s73, 10
	v_mov_b32_e32 v0, 0
	s_mov_b32 s57, -2
	v_add_u32_e32 v132, v2, v4
	v_add_u32_e32 v133, v2, v5
	v_add_u32_e32 v134, v7, v8
	v_add_u32_e32 v135, v7, v9
	v_add_u32_e32 v136, v10, v11
	v_add_u32_e32 v137, v10, v12
	v_add_u32_e32 v138, v3, v6
	v_add_u32_e32 v139, v3, v1
	s_mov_b64 s[42:43], s[50:51]
	v_mov_b32_e32 v1, v0
	v_mov_b32_e32 v2, v0
	v_mov_b32_e32 v3, v0
	v_mov_b32_e32 v4, v0
	v_mov_b32_e32 v5, v0
	v_mov_b32_e32 v6, v0
	v_mov_b32_e32 v7, v0
	v_mov_b32_e32 v8, v0
	v_mov_b32_e32 v9, v0
	v_mov_b32_e32 v10, v0
	v_mov_b32_e32 v11, v0
	v_mov_b32_e32 v12, v0
	v_mov_b32_e32 v13, v0
	v_mov_b32_e32 v14, v0
	v_mov_b32_e32 v15, v0
	v_mov_b32_e32 v16, v0
	v_mov_b32_e32 v17, v0
	v_mov_b32_e32 v18, v0
	v_mov_b32_e32 v19, v0
	v_mov_b32_e32 v20, v0
	v_mov_b32_e32 v21, v0
	v_mov_b32_e32 v22, v0
	v_mov_b32_e32 v23, v0
	v_mov_b32_e32 v24, v0
	v_mov_b32_e32 v25, v0
	v_mov_b32_e32 v26, v0
	v_mov_b32_e32 v27, v0
	v_mov_b32_e32 v28, v0
	v_mov_b32_e32 v29, v0
	v_mov_b32_e32 v30, v0
	v_mov_b32_e32 v31, v0
	v_mov_b32_e32 v32, v0
	v_mov_b32_e32 v33, v0
	v_mov_b32_e32 v34, v0
	v_mov_b32_e32 v35, v0
	v_mov_b32_e32 v36, v0
	v_mov_b32_e32 v37, v0
	v_mov_b32_e32 v38, v0
	v_mov_b32_e32 v39, v0
	v_mov_b32_e32 v40, v0
	v_mov_b32_e32 v41, v0
	v_mov_b32_e32 v42, v0
	v_mov_b32_e32 v43, v0
	v_mov_b32_e32 v44, v0
	v_mov_b32_e32 v45, v0
	v_mov_b32_e32 v46, v0
	v_mov_b32_e32 v47, v0
	v_mov_b32_e32 v48, v0
	v_mov_b32_e32 v49, v0
	v_mov_b32_e32 v50, v0
	v_mov_b32_e32 v51, v0
	v_mov_b32_e32 v52, v0
	v_mov_b32_e32 v53, v0
	v_mov_b32_e32 v54, v0
	v_mov_b32_e32 v55, v0
	v_mov_b32_e32 v56, v0
	v_mov_b32_e32 v57, v0
	v_mov_b32_e32 v58, v0
	v_mov_b32_e32 v59, v0
	v_mov_b32_e32 v60, v0
	v_mov_b32_e32 v61, v0
	v_mov_b32_e32 v62, v0
	v_mov_b32_e32 v63, v0
	v_mov_b32_e32 v64, v0
	v_mov_b32_e32 v65, v0
	v_mov_b32_e32 v66, v0
	v_mov_b32_e32 v67, v0
	v_mov_b32_e32 v68, v0
	v_mov_b32_e32 v69, v0
	v_mov_b32_e32 v70, v0
	v_mov_b32_e32 v71, v0
	v_mov_b32_e32 v72, v0
	v_mov_b32_e32 v73, v0
	v_mov_b32_e32 v74, v0
	v_mov_b32_e32 v75, v0
	v_mov_b32_e32 v76, v0
	v_mov_b32_e32 v77, v0
	v_mov_b32_e32 v78, v0
	v_mov_b32_e32 v79, v0
	v_mov_b32_e32 v80, v0
	v_mov_b32_e32 v81, v0
	v_mov_b32_e32 v82, v0
	v_mov_b32_e32 v83, v0
	v_mov_b32_e32 v84, v0
	v_mov_b32_e32 v85, v0
	v_mov_b32_e32 v86, v0
	v_mov_b32_e32 v87, v0
	v_mov_b32_e32 v88, v0
	v_mov_b32_e32 v89, v0
	v_mov_b32_e32 v90, v0
	v_mov_b32_e32 v91, v0
	v_mov_b32_e32 v92, v0
	v_mov_b32_e32 v93, v0
	v_mov_b32_e32 v94, v0
	v_mov_b32_e32 v95, v0
	v_mov_b32_e32 v96, v0
	v_mov_b32_e32 v97, v0
	v_mov_b32_e32 v98, v0
	v_mov_b32_e32 v99, v0
	v_mov_b32_e32 v100, v0
	v_mov_b32_e32 v101, v0
	v_mov_b32_e32 v102, v0
	v_mov_b32_e32 v103, v0
	v_mov_b32_e32 v104, v0
	v_mov_b32_e32 v105, v0
	v_mov_b32_e32 v106, v0
	v_mov_b32_e32 v107, v0
	v_mov_b32_e32 v108, v0
	v_mov_b32_e32 v109, v0
	v_mov_b32_e32 v110, v0
	v_mov_b32_e32 v111, v0
	v_mov_b32_e32 v112, v0
	v_mov_b32_e32 v113, v0
	v_mov_b32_e32 v114, v0
	v_mov_b32_e32 v115, v0
	v_mov_b32_e32 v116, v0
	v_mov_b32_e32 v117, v0
	v_mov_b32_e32 v118, v0
	v_mov_b32_e32 v119, v0
	v_mov_b32_e32 v120, v0
	v_mov_b32_e32 v121, v0
	v_mov_b32_e32 v122, v0
	v_mov_b32_e32 v123, v0
	v_mov_b32_e32 v124, v0
	v_mov_b32_e32 v125, v0
	v_mov_b32_e32 v126, v0
	v_mov_b32_e32 v127, v0
	s_barrier
	v_add_u32_e32 v164, v156, v160
	v_add_u32_e32 v165, v156, v161
	v_add_u32_e32 v166, v156, v162
	v_add_u32_e32 v167, v156, v163
	ds_read_b128 v[174:177], v164
	ds_read_b128 v[178:181], v165
	ds_read_b128 v[182:185], v166
	ds_read_b128 v[186:189], v167
; #define LDA(dst, b, h) for (int m = 0; m < 4; ++m) for (int k = 0; k < 2; ++k) \
;     dst[m][k] = *reinterpret_cast<const bf16x8*>((char*)SA(b, h) + lds_byte(wr * 64 + m * 16 + fr, k * 32 + fq * 8))
; #define LDB(dst, b, h) for (int n = 0; n < 2; ++n) for (int k = 0; k < 2; ++k) \
;     dst[n][k] = *reinterpret_cast<const bf16x8*>((char*)SB(b, h) + lds_byte(wc * 32 + n * 16 + fr, k * 32 + fq * 8))
; #define MMA(ai, bj, At_, Bt_) do { __builtin_amdgcn_s_setprio(1); \
;     for (int m = 0; m < 4; ++m) for (int n = 0; n < 2; ++n) for (int k = 0; k < 2; ++k) \
;       acc[ai][bj][m][n] = MFMA16(Bt_[n][k], At_[m][k], acc[ai][bj][m][n]); \
;     __builtin_amdgcn_s_setprio(0); } while (0)
; #define WAIT_V(n) asm volatile("s_waitcnt vmcnt(" #n ")" ::: "memory")
; #define WAIT_L(n) asm volatile("s_waitcnt lgkmcnt(" #n ")" ::: "memory")
; #define BAR __builtin_amdgcn_s_barrier()
; #define SCHED __builtin_amdgcn_sched_barrier(0)
; template <int PART  , bool SYNC_FIRST = true>
; __device__ __forceinline__ void kloop_t(const u16* __restrict__ A, int lda, const u16* __restrict__ Bt, int ldb, int K, Acc& acc, const int wv) {
;     ...
;     LDB(B0, 0, 0); SCHED; LDA(At, 0, 0); STAGE(SA(1, 1), A, lda, HALF, t + 1);
;     WAIT_L(8); BAR; WAIT_L(0); MMA(0, 0, At, B0); BAR; SCHED;
;     LDB(B1, 0, 1); STAGE(SB(0, 0), Bt, ldb, 0, t + 2);
;     BAR; WAIT_L(0); MMA(0, 1, At, B1); BAR;
;     LDA(At, 0, 1); STAGE(SA(0, 0), A, lda, 0, t + 2);
;     BAR; WAIT_L(0); MMA(1, 0, At, B0); BAR; SCHED;
;     STAGE(SB(0, 1), Bt, ldb, HALF, t + 2);
;     WAIT_V(6); BAR; MMA(1, 1, At, B1); BAR;
.LBB0_1139:
	s_add_u32 s44, s42, s56
	v_mov_b32_e32 v170, v131
	v_mov_b32_e32 v128, v130
	s_addc_u32 s45, s43, 0
	ds_read_b128 v[190:193], v132
	ds_read_b128 v[194:197], v133
	ds_read_b128 v[198:201], v134
	ds_read_b128 v[202:205], v135
	ds_read_b128 v[206:209], v136
	ds_read_b128 v[210:213], v137
	ds_read_b128 v[214:217], v138
	ds_read_b128 v[218:221], v139
	v_mov_b32_e32 v171, v129
	v_lshl_add_u64 v[168:169], s[44:45], 0, v[128:129]
	v_lshl_add_u64 v[172:173], v[168:169], 0, s[24:25]
	v_add_u32_e32 v168, 0xc000, v144
	v_add_u32_e32 v169, 0xe000, v144
	v_readfirstlane_b32 s52, v168
	s_mov_b32 m0, s52
	v_lshl_add_u64 v[170:171], s[44:45], 0, v[170:171]
	v_readfirstlane_b32 s52, v169
	global_load_lds_dwordx4 v[172:173], off
	v_lshl_add_u64 v[170:171], v[170:171], 0, s[24:25]
	s_mov_b32 m0, s52
	s_nop 0
	global_load_lds_dwordx4 v[170:171], off
	s_waitcnt lgkmcnt(8)
	s_barrier
	s_waitcnt lgkmcnt(0)
	s_setprio 1
	s_waitcnt lgkmcnt(0)
	v_mfma_f32_16x16x32_bf16 v[124:127], v[174:177], v[190:193], v[124:127]
	v_mfma_f32_16x16x32_bf16 v[120:123], v[182:185], v[190:193], v[120:123]
	v_mfma_f32_16x16x32_bf16 v[116:119], v[174:177], v[198:201], v[116:119]
	v_mfma_f32_16x16x32_bf16 v[112:115], v[182:185], v[198:201], v[112:115]
	v_mfma_f32_16x16x32_bf16 v[108:111], v[174:177], v[206:209], v[108:111]
	v_mfma_f32_16x16x32_bf16 v[104:107], v[182:185], v[206:209], v[104:107]
	v_mfma_f32_16x16x32_bf16 v[100:103], v[174:177], v[214:217], v[100:103]
	v_mfma_f32_16x16x32_bf16 v[96:99], v[182:185], v[214:217], v[96:99]
	v_mfma_f32_16x16x32_bf16 v[124:127], v[178:181], v[194:197], v[124:127]
	v_mfma_f32_16x16x32_bf16 v[120:123], v[186:189], v[194:197], v[120:123]
	v_mfma_f32_16x16x32_bf16 v[116:119], v[178:181], v[202:205], v[116:119]
	v_mfma_f32_16x16x32_bf16 v[112:115], v[186:189], v[202:205], v[112:115]
	v_mfma_f32_16x16x32_bf16 v[108:111], v[178:181], v[210:213], v[108:111]
	v_mfma_f32_16x16x32_bf16 v[104:107], v[186:189], v[210:213], v[104:107]
	v_mfma_f32_16x16x32_bf16 v[100:103], v[178:181], v[218:221], v[100:103]
	v_mfma_f32_16x16x32_bf16 v[96:99], v[186:189], v[218:221], v[96:99]
	s_setprio 0
	s_barrier
	s_add_u32 s52, s42, s55
	v_add_u32_e32 v170, v157, v160
	v_add_u32_e32 v172, v157, v162
	v_mov_b32_e32 v238, v131
	v_mov_b32_e32 v128, v130
	s_addc_u32 s53, s43, 0
	v_add_u32_e32 v171, v157, v161
	ds_read_b128 v[222:225], v170
	ds_read_b128 v[226:229], v171
	v_add_u32_e32 v173, v157, v163
	ds_read_b128 v[230:233], v172
	ds_read_b128 v[234:237], v173
	v_readfirstlane_b32 s87, v142
	v_lshl_add_u64 v[240:241], s[52:53], 0, v[128:129]
	v_mov_b32_e32 v239, v129
	v_lshl_add_u64 v[240:241], v[240:241], 0, s[26:27]
	s_mov_b32 m0, s87
	v_lshl_add_u64 v[238:239], s[52:53], 0, v[238:239]
	v_readfirstlane_b32 s87, v143
	global_load_lds_dwordx4 v[240:241], off
	v_lshl_add_u64 v[238:239], v[238:239], 0, s[26:27]
	s_mov_b32 m0, s87
	s_nop 0
	global_load_lds_dwordx4 v[238:239], off
	s_barrier
	s_waitcnt lgkmcnt(0)
	s_setprio 1
	s_waitcnt lgkmcnt(0)
	v_mfma_f32_16x16x32_bf16 v[92:95], v[222:225], v[190:193], v[92:95]
	v_mfma_f32_16x16x32_bf16 v[88:91], v[230:233], v[190:193], v[88:91]
	v_mfma_f32_16x16x32_bf16 v[84:87], v[222:225], v[198:201], v[84:87]
	v_mfma_f32_16x16x32_bf16 v[80:83], v[230:233], v[198:201], v[80:83]
	v_mfma_f32_16x16x32_bf16 v[76:79], v[222:225], v[206:209], v[76:79]
	v_mfma_f32_16x16x32_bf16 v[72:75], v[230:233], v[206:209], v[72:75]
	v_mfma_f32_16x16x32_bf16 v[68:71], v[222:225], v[214:217], v[68:71]
	v_mfma_f32_16x16x32_bf16 v[64:67], v[230:233], v[214:217], v[64:67]
	v_mfma_f32_16x16x32_bf16 v[92:95], v[226:229], v[194:197], v[92:95]
	v_mfma_f32_16x16x32_bf16 v[88:91], v[234:237], v[194:197], v[88:91]
	v_mfma_f32_16x16x32_bf16 v[84:87], v[226:229], v[202:205], v[84:87]
	v_mfma_f32_16x16x32_bf16 v[80:83], v[234:237], v[202:205], v[80:83]
	v_mfma_f32_16x16x32_bf16 v[76:79], v[226:229], v[210:213], v[76:79]
	v_mfma_f32_16x16x32_bf16 v[72:75], v[234:237], v[210:213], v[72:75]
	v_mfma_f32_16x16x32_bf16 v[68:71], v[226:229], v[218:221], v[68:71]
	v_mfma_f32_16x16x32_bf16 v[64:67], v[234:237], v[218:221], v[64:67]
	s_setprio 0
	v_mov_b32_e32 v238, v131
	v_mov_b32_e32 v128, v130
	s_barrier
	ds_read_b128 v[190:193], v132 offset:16384
	ds_read_b128 v[194:197], v133 offset:16384
	ds_read_b128 v[198:201], v134 offset:16384
	ds_read_b128 v[202:205], v135 offset:16384
	ds_read_b128 v[206:209], v136 offset:16384
	ds_read_b128 v[210:213], v137 offset:16384
	ds_read_b128 v[214:217], v138 offset:16384
	ds_read_b128 v[218:221], v139 offset:16384
	v_readfirstlane_b32 s87, v144
	v_lshl_add_u64 v[240:241], s[44:45], 0, v[128:129]
	v_mov_b32_e32 v239, v129
	v_lshl_add_u64 v[240:241], v[240:241], 0, s[28:29]
	s_mov_b32 m0, s87
	v_lshl_add_u64 v[238:239], s[44:45], 0, v[238:239]
	v_readfirstlane_b32 s87, v145
	global_load_lds_dwordx4 v[240:241], off
	v_lshl_add_u64 v[238:239], v[238:239], 0, s[28:29]
	s_mov_b32 m0, s87
	s_nop 0
	global_load_lds_dwordx4 v[238:239], off
	s_waitcnt vmcnt(10)
	s_barrier
	s_waitcnt lgkmcnt(0)
	s_setprio 1
	s_waitcnt lgkmcnt(0)
	v_mfma_f32_16x16x32_bf16 v[60:63], v[174:177], v[190:193], v[60:63]
	v_mfma_f32_16x16x32_bf16 v[56:59], v[182:185], v[190:193], v[56:59]
	v_mfma_f32_16x16x32_bf16 v[52:55], v[174:177], v[198:201], v[52:55]
	v_mfma_f32_16x16x32_bf16 v[48:51], v[182:185], v[198:201], v[48:51]
	v_mfma_f32_16x16x32_bf16 v[44:47], v[174:177], v[206:209], v[44:47]
	v_mfma_f32_16x16x32_bf16 v[40:43], v[182:185], v[206:209], v[40:43]
	v_mfma_f32_16x16x32_bf16 v[36:39], v[174:177], v[214:217], v[36:39]
	v_mfma_f32_16x16x32_bf16 v[32:35], v[182:185], v[214:217], v[32:35]
	v_mfma_f32_16x16x32_bf16 v[60:63], v[178:181], v[194:197], v[60:63]
	v_mfma_f32_16x16x32_bf16 v[56:59], v[186:189], v[194:197], v[56:59]
	v_mfma_f32_16x16x32_bf16 v[52:55], v[178:181], v[202:205], v[52:55]
	v_mfma_f32_16x16x32_bf16 v[48:51], v[186:189], v[202:205], v[48:51]
	v_mfma_f32_16x16x32_bf16 v[44:47], v[178:181], v[210:213], v[44:47]
	v_mfma_f32_16x16x32_bf16 v[40:43], v[186:189], v[210:213], v[40:43]
	v_mfma_f32_16x16x32_bf16 v[36:39], v[178:181], v[218:221], v[36:39]
	v_mfma_f32_16x16x32_bf16 v[32:35], v[186:189], v[218:221], v[32:35]
	s_setprio 0
	s_barrier
; #define LDA(dst, b, h) for (int m = 0; m < 4; ++m) for (int k = 0; k < 2; ++k) \
;     dst[m][k] = *reinterpret_cast<const bf16x8*>((char*)SA(b, h) + lds_byte(wr * 64 + m * 16 + fr, k * 32 + fq * 8))
; #define LDB(dst, b, h) for (int n = 0; n < 2; ++n) for (int k = 0; k < 2; ++k) \
;     dst[n][k] = *reinterpret_cast<const bf16x8*>((char*)SB(b, h) + lds_byte(wc * 32 + n * 16 + fr, k * 32 + fq * 8))
; #define MMA(ai, bj, At_, Bt_) do { __builtin_amdgcn_s_setprio(1); \
;     for (int m = 0; m < 4; ++m) for (int n = 0; n < 2; ++n) for (int k = 0; k < 2; ++k) \
;       acc[ai][bj][m][n] = MFMA16(Bt_[n][k], At_[m][k], acc[ai][bj][m][n]); \
;     __builtin_amdgcn_s_setprio(0); } while (0)
; #define WAIT_V(n) asm volatile("s_waitcnt vmcnt(" #n ")" ::: "memory")
; #define WAIT_L(n) asm volatile("s_waitcnt lgkmcnt(" #n ")" ::: "memory")
; #define BAR __builtin_amdgcn_s_barrier()
; #define SCHED __builtin_amdgcn_sched_barrier(0)
; template <int PART  , bool SYNC_FIRST = true>
; __device__ __forceinline__ void kloop_t(const u16* __restrict__ A, int lda, const u16* __restrict__ Bt, int ldb, int K, Acc& acc, const int wv) {
;     ...
;     WAIT_V(6); BAR; MMA(1, 1, At, B1); BAR;
;     LDB(B0, 1, 0); SCHED; LDA(At, 1, 0); STAGE(SA(0, 1), A, lda, HALF, t + 2);
;     WAIT_L(8); BAR; WAIT_L(0); MMA(0, 0, At, B0); BAR; SCHED;
	v_mov_b32_e32 v174, v131
	v_mov_b32_e32 v128, v130
	v_readfirstlane_b32 s87, v146
	v_lshl_add_u64 v[176:177], s[52:53], 0, v[128:129]
	v_mov_b32_e32 v175, v129
	v_lshl_add_u64 v[176:177], v[176:177], 0, s[30:31]
	s_mov_b32 m0, s87
	v_lshl_add_u64 v[174:175], s[52:53], 0, v[174:175]
	v_readfirstlane_b32 s87, v147
	global_load_lds_dwordx4 v[176:177], off
	v_lshl_add_u64 v[174:175], v[174:175], 0, s[30:31]
	s_mov_b32 m0, s87
	s_nop 0
	global_load_lds_dwordx4 v[174:175], off
	v_add_u32_e32 v174, v158, v160
	v_add_u32_e32 v175, v158, v161
	v_add_u32_e32 v176, v158, v162
	v_add_u32_e32 v177, v158, v163
	s_waitcnt vmcnt(6)
	s_barrier
	s_setprio 1
	v_mfma_f32_16x16x32_bf16 v[28:31], v[222:225], v[190:193], v[28:31]
	v_mfma_f32_16x16x32_bf16 v[24:27], v[230:233], v[190:193], v[24:27]
	ds_read_b128 v[182:185], v174
	ds_read_b128 v[186:189], v175
	ds_read_b128 v[190:193], v176
	v_mfma_f32_16x16x32_bf16 v[20:23], v[222:225], v[198:201], v[20:23]
	v_mfma_f32_16x16x32_bf16 v[16:19], v[230:233], v[198:201], v[16:19]
	v_mfma_f32_16x16x32_bf16 v[12:15], v[222:225], v[206:209], v[12:15]
	v_mfma_f32_16x16x32_bf16 v[8:11], v[230:233], v[206:209], v[8:11]
	v_mfma_f32_16x16x32_bf16 v[4:7], v[222:225], v[214:217], v[4:7]
	v_mfma_f32_16x16x32_bf16 v[0:3], v[230:233], v[214:217], v[0:3]
	v_mfma_f32_16x16x32_bf16 v[28:31], v[226:229], v[194:197], v[28:31]
	v_mfma_f32_16x16x32_bf16 v[24:27], v[234:237], v[194:197], v[24:27]
	ds_read_b128 v[194:197], v177
	v_mfma_f32_16x16x32_bf16 v[20:23], v[226:229], v[202:205], v[20:23]
	v_mfma_f32_16x16x32_bf16 v[16:19], v[234:237], v[202:205], v[16:19]
	v_mfma_f32_16x16x32_bf16 v[12:15], v[226:229], v[210:213], v[12:15]
	v_mfma_f32_16x16x32_bf16 v[8:11], v[234:237], v[210:213], v[8:11]
	v_mfma_f32_16x16x32_bf16 v[4:7], v[226:229], v[218:221], v[4:7]
	v_mfma_f32_16x16x32_bf16 v[0:3], v[234:237], v[218:221], v[0:3]
	s_setprio 0
	s_barrier
	v_mov_b32_e32 v178, v131
	v_mov_b32_e32 v128, v130
	ds_read_b128 v[198:201], v132 offset:32768
	ds_read_b128 v[202:205], v133 offset:32768
	ds_read_b128 v[206:209], v134 offset:32768
	ds_read_b128 v[210:213], v135 offset:32768
	ds_read_b128 v[214:217], v136 offset:32768
	ds_read_b128 v[218:221], v137 offset:32768
	ds_read_b128 v[222:225], v138 offset:32768
	ds_read_b128 v[226:229], v139 offset:32768
	v_readfirstlane_b32 s87, v148
	v_lshl_add_u64 v[180:181], s[44:45], 0, v[128:129]
	v_mov_b32_e32 v179, v129
	v_lshl_add_u64 v[180:181], v[180:181], 0, s[34:35]
	s_mov_b32 m0, s87
	v_lshl_add_u64 v[178:179], s[44:45], 0, v[178:179]
	v_readfirstlane_b32 s87, v149
	global_load_lds_dwordx4 v[180:181], off
	v_lshl_add_u64 v[178:179], v[178:179], 0, s[34:35]
	s_mov_b32 m0, s87
	s_nop 0
	global_load_lds_dwordx4 v[178:179], off
	s_waitcnt lgkmcnt(8)
	s_barrier
	s_waitcnt lgkmcnt(0)
	s_setprio 1
	s_waitcnt lgkmcnt(0)
	v_mfma_f32_16x16x32_bf16 v[124:127], v[182:185], v[198:201], v[124:127]
	v_mfma_f32_16x16x32_bf16 v[120:123], v[190:193], v[198:201], v[120:123]
	v_mfma_f32_16x16x32_bf16 v[116:119], v[182:185], v[206:209], v[116:119]
	v_mfma_f32_16x16x32_bf16 v[112:115], v[190:193], v[206:209], v[112:115]
	v_mfma_f32_16x16x32_bf16 v[108:111], v[182:185], v[214:217], v[108:111]
	v_mfma_f32_16x16x32_bf16 v[104:107], v[190:193], v[214:217], v[104:107]
	v_mfma_f32_16x16x32_bf16 v[100:103], v[182:185], v[222:225], v[100:103]
	v_mfma_f32_16x16x32_bf16 v[96:99], v[190:193], v[222:225], v[96:99]
	v_mfma_f32_16x16x32_bf16 v[124:127], v[186:189], v[202:205], v[124:127]
	v_mfma_f32_16x16x32_bf16 v[120:123], v[194:197], v[202:205], v[120:123]
	v_mfma_f32_16x16x32_bf16 v[116:119], v[186:189], v[210:213], v[116:119]
	v_mfma_f32_16x16x32_bf16 v[112:115], v[194:197], v[210:213], v[112:115]
	v_mfma_f32_16x16x32_bf16 v[108:111], v[186:189], v[218:221], v[108:111]
	v_mfma_f32_16x16x32_bf16 v[104:107], v[194:197], v[218:221], v[104:107]
	v_mfma_f32_16x16x32_bf16 v[100:103], v[186:189], v[226:229], v[100:103]
	v_mfma_f32_16x16x32_bf16 v[96:99], v[194:197], v[226:229], v[96:99]
	s_setprio 0
	s_barrier
	v_add_u32_e32 v178, v159, v160
	v_add_u32_e32 v180, v159, v162
	v_mov_b32_e32 v246, v131
	v_mov_b32_e32 v128, v130
	v_add_u32_e32 v179, v159, v161
	ds_read_b128 v[230:233], v178
	ds_read_b128 v[234:237], v179
	v_add_u32_e32 v181, v159, v163
	ds_read_b128 v[238:241], v180
	ds_read_b128 v[242:245], v181
	v_readfirstlane_b32 s87, v150
	v_lshl_add_u64 v[248:249], s[52:53], 0, v[128:129]
	v_mov_b32_e32 v247, v129
	v_lshl_add_u64 v[248:249], v[248:249], 0, s[36:37]
	s_mov_b32 m0, s87
	v_lshl_add_u64 v[246:247], s[52:53], 0, v[246:247]
	v_readfirstlane_b32 s87, v151
	global_load_lds_dwordx4 v[248:249], off
	v_lshl_add_u64 v[246:247], v[246:247], 0, s[36:37]
	s_mov_b32 m0, s87
	s_nop 0
	global_load_lds_dwordx4 v[246:247], off
	s_barrier
	s_waitcnt lgkmcnt(0)
	s_setprio 1
	s_waitcnt lgkmcnt(0)
	v_mfma_f32_16x16x32_bf16 v[92:95], v[230:233], v[198:201], v[92:95]
	v_mfma_f32_16x16x32_bf16 v[88:91], v[238:241], v[198:201], v[88:91]
	v_mfma_f32_16x16x32_bf16 v[84:87], v[230:233], v[206:209], v[84:87]
	v_mfma_f32_16x16x32_bf16 v[80:83], v[238:241], v[206:209], v[80:83]
	v_mfma_f32_16x16x32_bf16 v[76:79], v[230:233], v[214:217], v[76:79]
	v_mfma_f32_16x16x32_bf16 v[72:75], v[238:241], v[214:217], v[72:75]
	v_mfma_f32_16x16x32_bf16 v[68:71], v[230:233], v[222:225], v[68:71]
	v_mfma_f32_16x16x32_bf16 v[64:67], v[238:241], v[222:225], v[64:67]
	v_mfma_f32_16x16x32_bf16 v[92:95], v[234:237], v[202:205], v[92:95]
	v_mfma_f32_16x16x32_bf16 v[88:91], v[242:245], v[202:205], v[88:91]
	v_mfma_f32_16x16x32_bf16 v[84:87], v[234:237], v[210:213], v[84:87]
	v_mfma_f32_16x16x32_bf16 v[80:83], v[242:245], v[210:213], v[80:83]
	v_mfma_f32_16x16x32_bf16 v[76:79], v[234:237], v[218:221], v[76:79]
	v_mfma_f32_16x16x32_bf16 v[72:75], v[242:245], v[218:221], v[72:75]
	v_mfma_f32_16x16x32_bf16 v[68:71], v[234:237], v[226:229], v[68:71]
	v_mfma_f32_16x16x32_bf16 v[64:67], v[242:245], v[226:229], v[64:67]
	s_setprio 0
	v_mov_b32_e32 v246, v131
	v_mov_b32_e32 v128, v130
	s_barrier
; #define LDA(dst, b, h) for (int m = 0; m < 4; ++m) for (int k = 0; k < 2; ++k) \
;     dst[m][k] = *reinterpret_cast<const bf16x8*>((char*)SA(b, h) + lds_byte(wr * 64 + m * 16 + fr, k * 32 + fq * 8))
; #define LDB(dst, b, h) for (int n = 0; n < 2; ++n) for (int k = 0; k < 2; ++k) \
;     dst[n][k] = *reinterpret_cast<const bf16x8*>((char*)SB(b, h) + lds_byte(wc * 32 + n * 16 + fr, k * 32 + fq * 8))
; #define MMA(ai, bj, At_, Bt_) do { __builtin_amdgcn_s_setprio(1); \
;     for (int m = 0; m < 4; ++m) for (int n = 0; n < 2; ++n) for (int k = 0; k < 2; ++k) \
;       acc[ai][bj][m][n] = MFMA16(Bt_[n][k], At_[m][k], acc[ai][bj][m][n]); \
;     __builtin_amdgcn_s_setprio(0); } while (0)
; #define WAIT_V(n) asm volatile("s_waitcnt vmcnt(" #n ")" ::: "memory")
; #define WAIT_L(n) asm volatile("s_waitcnt lgkmcnt(" #n ")" ::: "memory")
; #define BAR __builtin_amdgcn_s_barrier()
; #define SCHED __builtin_amdgcn_sched_barrier(0)
; template <int PART  , bool SYNC_FIRST = true>
; __device__ __forceinline__ void kloop_t(const u16* __restrict__ A, int lda, const u16* __restrict__ Bt, int ldb, int K, Acc& acc, const int wv) {
;     ...
;     WAIT_L(8); BAR; WAIT_L(0); MMA(0, 0, At, B0); BAR; SCHED;
;     LDB(B1, 1, 1); STAGE(SB(1, 0), Bt, ldb, 0, t + 3);
;     BAR; WAIT_L(0); MMA(0, 1, At, B1); BAR;
;     LDA(At, 1, 1); STAGE(SA(1, 0), A, lda, 0, t + 3);
;     BAR; WAIT_L(0); MMA(1, 0, At, B0); BAR; SCHED;
;     STAGE(SB(1, 1), Bt, ldb, HALF, t + 3);
;     WAIT_V(6); BAR; MMA(1, 1, At, B1); BAR;
;   }
;   { LDB(B0, 0, 0); LDA(At, 0, 0); STAGE(SA(1, 1), A, lda, HALF, nt - 1);
;     BAR; WAIT_L(0); MMA(0, 0, At, B0); BAR;
;     LDB(B1, 0, 1); BAR; WAIT_L(0); MMA(0, 1, At, B1); BAR;
;     LDA(At, 0, 1); WAIT_V(4); BAR; WAIT_L(0); MMA(1, 0, At, B0); MMA(1, 1, At, B1); BAR; }
	ds_read_b128 v[198:201], v132 offset:49152
	ds_read_b128 v[202:205], v133 offset:49152
	ds_read_b128 v[206:209], v134 offset:49152
	ds_read_b128 v[210:213], v135 offset:49152
	ds_read_b128 v[214:217], v136 offset:49152
	ds_read_b128 v[218:221], v137 offset:49152
	ds_read_b128 v[222:225], v138 offset:49152
	ds_read_b128 v[226:229], v139 offset:49152
	v_readfirstlane_b32 s87, v152
	v_lshl_add_u64 v[248:249], s[44:45], 0, v[128:129]
	v_mov_b32_e32 v247, v129
	v_lshl_add_u64 v[248:249], v[248:249], 0, s[38:39]
	s_mov_b32 m0, s87
	v_lshl_add_u64 v[246:247], s[44:45], 0, v[246:247]
	v_readfirstlane_b32 s44, v153
	global_load_lds_dwordx4 v[248:249], off
	v_lshl_add_u64 v[246:247], v[246:247], 0, s[38:39]
	s_mov_b32 m0, s44
	s_nop 0
	global_load_lds_dwordx4 v[246:247], off
	s_waitcnt vmcnt(10)
	s_barrier
	s_waitcnt lgkmcnt(0)
	s_setprio 1
	s_waitcnt lgkmcnt(0)
	v_mfma_f32_16x16x32_bf16 v[60:63], v[182:185], v[198:201], v[60:63]
	v_mfma_f32_16x16x32_bf16 v[56:59], v[190:193], v[198:201], v[56:59]
	v_mfma_f32_16x16x32_bf16 v[52:55], v[182:185], v[206:209], v[52:55]
	v_mfma_f32_16x16x32_bf16 v[48:51], v[190:193], v[206:209], v[48:51]
	v_mfma_f32_16x16x32_bf16 v[44:47], v[182:185], v[214:217], v[44:47]
	v_mfma_f32_16x16x32_bf16 v[40:43], v[190:193], v[214:217], v[40:43]
	v_mfma_f32_16x16x32_bf16 v[36:39], v[182:185], v[222:225], v[36:39]
	v_mfma_f32_16x16x32_bf16 v[32:35], v[190:193], v[222:225], v[32:35]
	v_mfma_f32_16x16x32_bf16 v[60:63], v[186:189], v[202:205], v[60:63]
	v_mfma_f32_16x16x32_bf16 v[56:59], v[194:197], v[202:205], v[56:59]
	v_mfma_f32_16x16x32_bf16 v[52:55], v[186:189], v[210:213], v[52:55]
	v_mfma_f32_16x16x32_bf16 v[48:51], v[194:197], v[210:213], v[48:51]
	v_mfma_f32_16x16x32_bf16 v[44:47], v[186:189], v[218:221], v[44:47]
	v_mfma_f32_16x16x32_bf16 v[40:43], v[194:197], v[218:221], v[40:43]
	v_mfma_f32_16x16x32_bf16 v[36:39], v[186:189], v[226:229], v[36:39]
	v_mfma_f32_16x16x32_bf16 v[32:35], v[194:197], v[226:229], v[32:35]
	s_setprio 0
	s_barrier
	v_mov_b32_e32 v182, v131
	v_mov_b32_e32 v128, v130
	v_readfirstlane_b32 s44, v154
	v_lshl_add_u64 v[184:185], s[52:53], 0, v[128:129]
	v_mov_b32_e32 v183, v129
	v_lshl_add_u64 v[184:185], v[184:185], 0, s[40:41]
	s_mov_b32 m0, s44
	v_lshl_add_u64 v[182:183], s[52:53], 0, v[182:183]
	v_readfirstlane_b32 s44, v155
	global_load_lds_dwordx4 v[184:185], off
	v_lshl_add_u64 v[182:183], v[182:183], 0, s[40:41]
	s_mov_b32 m0, s44
	s_nop 0
	global_load_lds_dwordx4 v[182:183], off
	s_waitcnt vmcnt(6)
	s_barrier
	s_setprio 1
	v_mfma_f32_16x16x32_bf16 v[28:31], v[230:233], v[198:201], v[28:31]
	v_mfma_f32_16x16x32_bf16 v[24:27], v[238:241], v[198:201], v[24:27]
	ds_read_b128 v[174:177], v164
	ds_read_b128 v[178:181], v165
	ds_read_b128 v[182:185], v166
	ds_read_b128 v[186:189], v167
	v_mfma_f32_16x16x32_bf16 v[20:23], v[230:233], v[206:209], v[20:23]
	v_mfma_f32_16x16x32_bf16 v[16:19], v[238:241], v[206:209], v[16:19]
	v_mfma_f32_16x16x32_bf16 v[12:15], v[230:233], v[214:217], v[12:15]
	v_mfma_f32_16x16x32_bf16 v[8:11], v[238:241], v[214:217], v[8:11]
	v_mfma_f32_16x16x32_bf16 v[4:7], v[230:233], v[222:225], v[4:7]
	v_mfma_f32_16x16x32_bf16 v[0:3], v[238:241], v[222:225], v[0:3]
	v_mfma_f32_16x16x32_bf16 v[28:31], v[234:237], v[202:205], v[28:31]
	v_mfma_f32_16x16x32_bf16 v[24:27], v[242:245], v[202:205], v[24:27]
	v_mfma_f32_16x16x32_bf16 v[20:23], v[234:237], v[210:213], v[20:23]
	v_mfma_f32_16x16x32_bf16 v[16:19], v[242:245], v[210:213], v[16:19]
	v_mfma_f32_16x16x32_bf16 v[12:15], v[234:237], v[218:221], v[12:15]
	v_mfma_f32_16x16x32_bf16 v[8:11], v[242:245], v[218:221], v[8:11]
	v_mfma_f32_16x16x32_bf16 v[4:7], v[234:237], v[226:229], v[4:7]
	v_mfma_f32_16x16x32_bf16 v[0:3], v[242:245], v[226:229], v[0:3]
	s_setprio 0
	s_add_i32 s57, s57, 2
	s_add_u32 s42, s42, 0x100
	s_addc_u32 s43, s43, 0
	s_cmp_lt_u32 s57, 60
	s_barrier
	s_cbranch_scc1 .LBB0_1139
	s_waitcnt lgkmcnt(0)
	v_add_u32_e32 v174, v158, v160
	v_add_u32_e32 v175, v158, v161
	v_add_u32_e32 v176, v158, v162
	v_add_u32_e32 v177, v158, v163
	v_add_u32_e32 v178, v159, v160
	v_add_u32_e32 v179, v159, v161
	v_add_u32_e32 v180, v159, v162
	v_add_u32_e32 v181, v159, v163
	s_add_u32 s4, s4, 0x101f80
	v_readfirstlane_b32 s42, v168
	s_addc_u32 s5, s5, 0
	s_mov_b32 m0, s42
	v_readfirstlane_b32 s42, v169
	ds_read_b128 v[142:145], v164
	ds_read_b128 v[146:149], v165
	ds_read_b128 v[150:153], v166
	ds_read_b128 v[154:157], v167
	ds_read_b128 v[158:161], v132
	ds_read_b128 v[162:165], v133
	ds_read_b128 v[182:185], v134
	ds_read_b128 v[186:189], v135
	ds_read_b128 v[190:193], v136
	ds_read_b128 v[194:197], v137
	ds_read_b128 v[198:201], v138
	ds_read_b128 v[202:205], v139
	s_nop 0
	global_load_lds_dwordx4 v130, s[4:5]
	s_mov_b32 m0, s42
	s_nop 0
	global_load_lds_dwordx4 v131, s[4:5]
	s_barrier
	s_waitcnt lgkmcnt(0)
	s_setprio 1
	s_waitcnt lgkmcnt(0)
	v_mfma_f32_16x16x32_bf16 v[124:127], v[142:145], v[158:161], v[124:127]
	v_mfma_f32_16x16x32_bf16 v[120:123], v[150:153], v[158:161], v[120:123]
	v_mfma_f32_16x16x32_bf16 v[108:111], v[142:145], v[190:193], v[108:111]
	v_mfma_f32_16x16x32_bf16 v[104:107], v[150:153], v[190:193], v[104:107]
	v_mfma_f32_16x16x32_bf16 v[124:127], v[146:149], v[162:165], v[124:127]
	v_mfma_f32_16x16x32_bf16 v[120:123], v[154:157], v[162:165], v[120:123]
	v_mfma_f32_16x16x32_bf16 v[116:119], v[142:145], v[182:185], v[116:119]
	v_mfma_f32_16x16x32_bf16 v[112:115], v[150:153], v[182:185], v[112:115]
	v_mfma_f32_16x16x32_bf16 v[108:111], v[146:149], v[194:197], v[108:111]
	v_mfma_f32_16x16x32_bf16 v[104:107], v[154:157], v[194:197], v[104:107]
	v_mfma_f32_16x16x32_bf16 v[100:103], v[142:145], v[198:201], v[100:103]
	v_mfma_f32_16x16x32_bf16 v[96:99], v[150:153], v[198:201], v[96:99]
	v_mfma_f32_16x16x32_bf16 v[166:169], v[146:149], v[186:189], v[116:119]
	v_mfma_f32_16x16x32_bf16 v[206:209], v[154:157], v[186:189], v[112:115]
	v_mfma_f32_16x16x32_bf16 v[210:213], v[146:149], v[202:205], v[100:103]
	v_mfma_f32_16x16x32_bf16 v[214:217], v[154:157], v[202:205], v[96:99]
	s_setprio 0
	s_barrier
; #define LDA(dst, b, h) for (int m = 0; m < 4; ++m) for (int k = 0; k < 2; ++k) \
;     dst[m][k] = *reinterpret_cast<const bf16x8*>((char*)SA(b, h) + lds_byte(wr * 64 + m * 16 + fr, k * 32 + fq * 8))
; #define LDB(dst, b, h) for (int n = 0; n < 2; ++n) for (int k = 0; k < 2; ++k) \
;     dst[n][k] = *reinterpret_cast<const bf16x8*>((char*)SB(b, h) + lds_byte(wc * 32 + n * 16 + fr, k * 32 + fq * 8))
; #define MMA(ai, bj, At_, Bt_) do { __builtin_amdgcn_s_setprio(1); \
;     for (int m = 0; m < 4; ++m) for (int n = 0; n < 2; ++n) for (int k = 0; k < 2; ++k) \
;       acc[ai][bj][m][n] = MFMA16(Bt_[n][k], At_[m][k], acc[ai][bj][m][n]); \
;     __builtin_amdgcn_s_setprio(0); } while (0)
; #define WAIT_V(n) asm volatile("s_waitcnt vmcnt(" #n ")" ::: "memory")
; #define WAIT_L(n) asm volatile("s_waitcnt lgkmcnt(" #n ")" ::: "memory")
; #define BAR __builtin_amdgcn_s_barrier()
; template <int PART  , bool SYNC_FIRST = true>
; __device__ __forceinline__ void kloop_t(const u16* __restrict__ A, int lda, const u16* __restrict__ Bt, int ldb, int K, Acc& acc, const int wv) {
;     ...
;   { LDB(B0, 0, 0); LDA(At, 0, 0); STAGE(SA(1, 1), A, lda, HALF, nt - 1);
;     BAR; WAIT_L(0); MMA(0, 0, At, B0); BAR;
;     LDB(B1, 0, 1); BAR; WAIT_L(0); MMA(0, 1, At, B1); BAR;
;     LDA(At, 0, 1); WAIT_V(4); BAR; WAIT_L(0); MMA(1, 0, At, B0); MMA(1, 1, At, B1); BAR; }
;   { LDB(B0, 1, 0); LDA(At, 1, 0); WAIT_V(2); BAR; WAIT_L(0); MMA(0, 0, At, B0); BAR;
;     LDB(B1, 1, 1); WAIT_V(0); BAR; WAIT_L(0); MMA(0, 1, At, B1); BAR;
	s_nop 1
	ds_read_b128 v[96:99], v170
	ds_read_b128 v[100:103], v171
	ds_read_b128 v[112:115], v172
	ds_read_b128 v[116:119], v173
	s_barrier
	s_waitcnt lgkmcnt(0)
	s_setprio 1
	s_waitcnt lgkmcnt(0)
	v_mfma_f32_16x16x32_bf16 v[92:95], v[96:99], v[158:161], v[92:95]
	v_mfma_f32_16x16x32_bf16 v[88:91], v[112:115], v[158:161], v[88:91]
	v_mfma_f32_16x16x32_bf16 v[76:79], v[96:99], v[190:193], v[76:79]
	v_mfma_f32_16x16x32_bf16 v[72:75], v[112:115], v[190:193], v[72:75]
	v_mfma_f32_16x16x32_bf16 v[92:95], v[100:103], v[162:165], v[92:95]
	v_mfma_f32_16x16x32_bf16 v[88:91], v[116:119], v[162:165], v[88:91]
	v_mfma_f32_16x16x32_bf16 v[84:87], v[96:99], v[182:185], v[84:87]
	v_mfma_f32_16x16x32_bf16 v[80:83], v[112:115], v[182:185], v[80:83]
	v_mfma_f32_16x16x32_bf16 v[76:79], v[100:103], v[194:197], v[76:79]
	v_mfma_f32_16x16x32_bf16 v[72:75], v[116:119], v[194:197], v[72:75]
	v_mfma_f32_16x16x32_bf16 v[68:71], v[96:99], v[198:201], v[68:71]
	v_mfma_f32_16x16x32_bf16 v[64:67], v[112:115], v[198:201], v[64:67]
	v_mfma_f32_16x16x32_bf16 v[158:161], v[100:103], v[186:189], v[84:87]
	v_mfma_f32_16x16x32_bf16 v[162:165], v[116:119], v[186:189], v[80:83]
	v_mfma_f32_16x16x32_bf16 v[170:173], v[100:103], v[202:205], v[68:71]
	v_mfma_f32_16x16x32_bf16 v[182:185], v[116:119], v[202:205], v[64:67]
	s_setprio 0
	s_barrier
	s_nop 1
	ds_read_b128 v[64:67], v132 offset:16384
	ds_read_b128 v[68:71], v133 offset:16384
	ds_read_b128 v[80:83], v134 offset:16384
	ds_read_b128 v[84:87], v135 offset:16384
	ds_read_b128 v[186:189], v136 offset:16384
	ds_read_b128 v[190:193], v137 offset:16384
	ds_read_b128 v[194:197], v138 offset:16384
	ds_read_b128 v[198:201], v139 offset:16384
	s_waitcnt vmcnt(4)
	s_barrier
	s_waitcnt lgkmcnt(0)
	s_setprio 1
	s_waitcnt lgkmcnt(0)
	v_mfma_f32_16x16x32_bf16 v[60:63], v[142:145], v[64:67], v[60:63]
	v_mfma_f32_16x16x32_bf16 v[56:59], v[150:153], v[64:67], v[56:59]
	v_mfma_f32_16x16x32_bf16 v[44:47], v[142:145], v[186:189], v[44:47]
	v_mfma_f32_16x16x32_bf16 v[40:43], v[150:153], v[186:189], v[40:43]
	v_mfma_f32_16x16x32_bf16 v[60:63], v[146:149], v[68:71], v[60:63]
	v_mfma_f32_16x16x32_bf16 v[56:59], v[154:157], v[68:71], v[56:59]
	v_mfma_f32_16x16x32_bf16 v[52:55], v[142:145], v[80:83], v[52:55]
	v_mfma_f32_16x16x32_bf16 v[48:51], v[150:153], v[80:83], v[48:51]
	v_mfma_f32_16x16x32_bf16 v[44:47], v[146:149], v[190:193], v[44:47]
	v_mfma_f32_16x16x32_bf16 v[40:43], v[154:157], v[190:193], v[40:43]
	v_mfma_f32_16x16x32_bf16 v[36:39], v[142:145], v[194:197], v[36:39]
	v_mfma_f32_16x16x32_bf16 v[32:35], v[150:153], v[194:197], v[32:35]
	v_mfma_f32_16x16x32_bf16 v[202:205], v[146:149], v[84:87], v[52:55]
	v_mfma_f32_16x16x32_bf16 v[218:221], v[154:157], v[84:87], v[48:51]
	v_mfma_f32_16x16x32_bf16 v[142:145], v[146:149], v[198:201], v[36:39]
	v_mfma_f32_16x16x32_bf16 v[146:149], v[154:157], v[198:201], v[32:35]
	s_setprio 0
	s_setprio 1
	v_mfma_f32_16x16x32_bf16 v[28:31], v[96:99], v[64:67], v[28:31]
	v_mfma_f32_16x16x32_bf16 v[24:27], v[112:115], v[64:67], v[24:27]
	v_mfma_f32_16x16x32_bf16 v[12:15], v[96:99], v[186:189], v[12:15]
	v_mfma_f32_16x16x32_bf16 v[8:11], v[112:115], v[186:189], v[8:11]
	v_mfma_f32_16x16x32_bf16 v[28:31], v[100:103], v[68:71], v[28:31]
	v_mfma_f32_16x16x32_bf16 v[24:27], v[116:119], v[68:71], v[24:27]
	v_mfma_f32_16x16x32_bf16 v[20:23], v[96:99], v[80:83], v[20:23]
	v_mfma_f32_16x16x32_bf16 v[16:19], v[112:115], v[80:83], v[16:19]
	v_mfma_f32_16x16x32_bf16 v[12:15], v[100:103], v[190:193], v[12:15]
	v_mfma_f32_16x16x32_bf16 v[8:11], v[116:119], v[190:193], v[8:11]
	v_mfma_f32_16x16x32_bf16 v[4:7], v[96:99], v[194:197], v[4:7]
	v_mfma_f32_16x16x32_bf16 v[0:3], v[112:115], v[194:197], v[0:3]
	v_mfma_f32_16x16x32_bf16 v[150:153], v[100:103], v[84:87], v[20:23]
	v_mfma_f32_16x16x32_bf16 v[154:157], v[116:119], v[84:87], v[16:19]
	v_mfma_f32_16x16x32_bf16 v[186:189], v[100:103], v[198:201], v[4:7]
	v_mfma_f32_16x16x32_bf16 v[190:193], v[116:119], v[198:201], v[0:3]
	s_setprio 0
	s_barrier
	s_nop 1
	ds_read_b128 v[0:3], v174
	ds_read_b128 v[4:7], v175
	ds_read_b128 v[194:197], v176
	ds_read_b128 v[174:177], v177
	ds_read_b128 v[16:19], v132 offset:32768
	ds_read_b128 v[20:23], v133 offset:32768
	ds_read_b128 v[32:35], v134 offset:32768
	ds_read_b128 v[36:39], v135 offset:32768
	ds_read_b128 v[48:51], v136 offset:32768
	ds_read_b128 v[52:55], v137 offset:32768
	ds_read_b128 v[198:201], v138 offset:32768
	ds_read_b128 v[222:225], v139 offset:32768
	s_waitcnt vmcnt(2)
	s_barrier
; #define LDA(dst, b, h) for (int m = 0; m < 4; ++m) for (int k = 0; k < 2; ++k) \
;     dst[m][k] = *reinterpret_cast<const bf16x8*>((char*)SA(b, h) + lds_byte(wr * 64 + m * 16 + fr, k * 32 + fq * 8))
; #define LDB(dst, b, h) for (int n = 0; n < 2; ++n) for (int k = 0; k < 2; ++k) \
;     dst[n][k] = *reinterpret_cast<const bf16x8*>((char*)SB(b, h) + lds_byte(wc * 32 + n * 16 + fr, k * 32 + fq * 8))
; #define MMA(ai, bj, At_, Bt_) do { __builtin_amdgcn_s_setprio(1); \
;     for (int m = 0; m < 4; ++m) for (int n = 0; n < 2; ++n) for (int k = 0; k < 2; ++k) \
;       acc[ai][bj][m][n] = MFMA16(Bt_[n][k], At_[m][k], acc[ai][bj][m][n]); \
;     __builtin_amdgcn_s_setprio(0); } while (0)
; #define WAIT_V(n) asm volatile("s_waitcnt vmcnt(" #n ")" ::: "memory")
; #define WAIT_L(n) asm volatile("s_waitcnt lgkmcnt(" #n ")" ::: "memory")
; #define BAR __builtin_amdgcn_s_barrier()
; template <int PART  , bool SYNC_FIRST = true>
; __device__ __forceinline__ void kloop_t(const u16* __restrict__ A, int lda, const u16* __restrict__ Bt, int ldb, int K, Acc& acc, const int wv) {
;     ...
;     LDA(At, 0, 1); WAIT_V(4); BAR; WAIT_L(0); MMA(1, 0, At, B0); MMA(1, 1, At, B1); BAR; }
;   { LDB(B0, 1, 0); LDA(At, 1, 0); WAIT_V(2); BAR; WAIT_L(0); MMA(0, 0, At, B0); BAR;
;     LDB(B1, 1, 1); WAIT_V(0); BAR; WAIT_L(0); MMA(0, 1, At, B1); BAR;
;     LDA(At, 1, 1); BAR; WAIT_L(0); MMA(1, 0, At, B0); MMA(1, 1, At, B1); BAR; }
;   if (wr == 0) BAR;
	s_waitcnt lgkmcnt(0)
	s_setprio 1
	s_waitcnt lgkmcnt(0)
	v_mfma_f32_16x16x32_bf16 v[64:67], v[0:3], v[16:19], v[124:127]
	v_mfma_f32_16x16x32_bf16 v[112:115], v[4:7], v[20:23], v[64:67]
	v_mfma_f32_16x16x32_bf16 v[64:67], v[194:197], v[16:19], v[120:123]
	v_mfma_f32_16x16x32_bf16 v[116:119], v[174:177], v[20:23], v[64:67]
	v_mfma_f32_16x16x32_bf16 v[64:67], v[0:3], v[32:35], v[166:169]
	v_mfma_f32_16x16x32_bf16 v[96:99], v[4:7], v[36:39], v[64:67]
	v_mfma_f32_16x16x32_bf16 v[64:67], v[194:197], v[32:35], v[206:209]
	v_mfma_f32_16x16x32_bf16 v[100:103], v[174:177], v[36:39], v[64:67]
	v_mfma_f32_16x16x32_bf16 v[64:67], v[0:3], v[48:51], v[108:111]
	v_mfma_f32_16x16x32_bf16 v[80:83], v[4:7], v[52:55], v[64:67]
	v_mfma_f32_16x16x32_bf16 v[64:67], v[194:197], v[48:51], v[104:107]
	v_mfma_f32_16x16x32_bf16 v[84:87], v[174:177], v[52:55], v[64:67]
	v_mfma_f32_16x16x32_bf16 v[64:67], v[0:3], v[198:201], v[210:213]
	v_mfma_f32_16x16x32_bf16 v[68:71], v[194:197], v[198:201], v[214:217]
	v_mfma_f32_16x16x32_bf16 v[64:67], v[4:7], v[222:225], v[64:67]
	v_mfma_f32_16x16x32_bf16 v[68:71], v[174:177], v[222:225], v[68:71]
	s_setprio 0
	s_barrier
	ds_read_b128 v[166:169], v178
	ds_read_b128 v[206:209], v179
	ds_read_b128 v[210:213], v180
	ds_read_b128 v[178:181], v181
	s_waitcnt vmcnt(0)
	s_barrier
	s_waitcnt lgkmcnt(0)
	s_setprio 1
	s_waitcnt lgkmcnt(0)
	v_mfma_f32_16x16x32_bf16 v[92:95], v[166:169], v[16:19], v[92:95]
	v_mfma_f32_16x16x32_bf16 v[16:19], v[210:213], v[16:19], v[88:91]
	v_mfma_f32_16x16x32_bf16 v[124:127], v[178:181], v[20:23], v[16:19]
	v_mfma_f32_16x16x32_bf16 v[16:19], v[166:169], v[32:35], v[158:161]
	v_mfma_f32_16x16x32_bf16 v[104:107], v[206:209], v[36:39], v[16:19]
	v_mfma_f32_16x16x32_bf16 v[16:19], v[210:213], v[32:35], v[162:165]
	v_mfma_f32_16x16x32_bf16 v[108:111], v[178:181], v[36:39], v[16:19]
	v_mfma_f32_16x16x32_bf16 v[16:19], v[166:169], v[48:51], v[76:79]
	v_mfma_f32_16x16x32_bf16 v[88:91], v[206:209], v[52:55], v[16:19]
	v_mfma_f32_16x16x32_bf16 v[16:19], v[210:213], v[48:51], v[72:75]
	v_mfma_f32_16x16x32_bf16 v[120:123], v[206:209], v[20:23], v[92:95]
	v_mfma_f32_16x16x32_bf16 v[92:95], v[178:181], v[52:55], v[16:19]
	v_mfma_f32_16x16x32_bf16 v[16:19], v[166:169], v[198:201], v[170:173]
	v_mfma_f32_16x16x32_bf16 v[72:75], v[206:209], v[222:225], v[16:19]
	v_mfma_f32_16x16x32_bf16 v[16:19], v[210:213], v[198:201], v[182:185]
	v_mfma_f32_16x16x32_bf16 v[76:79], v[178:181], v[222:225], v[16:19]
	s_setprio 0
	s_barrier
	ds_read_b128 v[158:161], v132 offset:49152
	ds_read_b128 v[130:133], v133 offset:49152
	ds_read_b128 v[162:165], v134 offset:49152
	ds_read_b128 v[170:173], v135 offset:49152
	ds_read_b128 v[182:185], v136 offset:49152
	ds_read_b128 v[134:137], v137 offset:49152
	ds_read_b128 v[198:201], v138 offset:49152
	ds_read_b128 v[214:217], v139 offset:49152
	s_barrier
	s_waitcnt lgkmcnt(0)
	s_setprio 1
	s_waitcnt lgkmcnt(0)
	v_mfma_f32_16x16x32_bf16 v[16:19], v[0:3], v[158:161], v[60:63]
	v_mfma_f32_16x16x32_bf16 v[48:51], v[4:7], v[130:133], v[16:19]
	v_mfma_f32_16x16x32_bf16 v[16:19], v[194:197], v[158:161], v[56:59]
	v_mfma_f32_16x16x32_bf16 v[52:55], v[174:177], v[130:133], v[16:19]
	v_mfma_f32_16x16x32_bf16 v[16:19], v[0:3], v[162:165], v[202:205]
	v_mfma_f32_16x16x32_bf16 v[32:35], v[4:7], v[170:173], v[16:19]
	v_mfma_f32_16x16x32_bf16 v[16:19], v[194:197], v[162:165], v[218:221]
	v_mfma_f32_16x16x32_bf16 v[36:39], v[174:177], v[170:173], v[16:19]
	v_mfma_f32_16x16x32_bf16 v[16:19], v[0:3], v[182:185], v[44:47]
	v_mfma_f32_16x16x32_bf16 v[0:3], v[0:3], v[198:201], v[142:145]
	v_mfma_f32_16x16x32_bf16 v[16:19], v[4:7], v[134:137], v[16:19]
	v_mfma_f32_16x16x32_bf16 v[20:23], v[194:197], v[182:185], v[40:43]
	v_mfma_f32_16x16x32_bf16 v[0:3], v[4:7], v[214:217], v[0:3]
	v_mfma_f32_16x16x32_bf16 v[4:7], v[194:197], v[198:201], v[146:149]
	v_mfma_f32_16x16x32_bf16 v[20:23], v[174:177], v[134:137], v[20:23]
	v_mfma_f32_16x16x32_bf16 v[4:7], v[174:177], v[214:217], v[4:7]
	s_setprio 0
	s_setprio 1
	v_mfma_f32_16x16x32_bf16 v[24:27], v[210:213], v[158:161], v[24:27]
	v_mfma_f32_16x16x32_bf16 v[60:63], v[178:181], v[130:133], v[24:27]
	v_mfma_f32_16x16x32_bf16 v[24:27], v[166:169], v[162:165], v[150:153]
	v_mfma_f32_16x16x32_bf16 v[28:31], v[166:169], v[158:161], v[28:31]
	v_mfma_f32_16x16x32_bf16 v[40:43], v[206:209], v[170:173], v[24:27]
	v_mfma_f32_16x16x32_bf16 v[24:27], v[210:213], v[162:165], v[154:157]
	v_mfma_f32_16x16x32_bf16 v[12:15], v[166:169], v[182:185], v[12:15]
	v_mfma_f32_16x16x32_bf16 v[8:11], v[210:213], v[182:185], v[8:11]
	v_mfma_f32_16x16x32_bf16 v[56:59], v[206:209], v[130:133], v[28:31]
	v_mfma_f32_16x16x32_bf16 v[44:47], v[178:181], v[170:173], v[24:27]
	v_mfma_f32_16x16x32_bf16 v[24:27], v[206:209], v[134:137], v[12:15]
	v_mfma_f32_16x16x32_bf16 v[28:31], v[178:181], v[134:137], v[8:11]
	v_mfma_f32_16x16x32_bf16 v[8:11], v[166:169], v[198:201], v[186:189]
	v_mfma_f32_16x16x32_bf16 v[12:15], v[210:213], v[198:201], v[190:193]
	v_mfma_f32_16x16x32_bf16 v[8:11], v[206:209], v[214:217], v[8:11]
	v_mfma_f32_16x16x32_bf16 v[12:15], v[178:181], v[214:217], v[12:15]
	s_setprio 0
	s_andn2_b64 vcc, exec, s[16:17]
	s_barrier
	s_cbranch_vccnz .LBB0_1142
	s_barrier
